# adds: sample mini-GEMM K loops fully unrolled with 14-step-deep load prefetch (P1 and P3), P0 LDS fill with 16 loads in flight, static s_setprio 1 for waves 4-7 in attention
# speedup vs baseline: 1.0157x; 1.0157x over previous
; #define LAS __attribute__((address_space(3)))
; __device__ __forceinline__ void phase0(const Params& P, LAS unsigned char* lds, int tid, int lane, int wave) {
;     const int G = gridDim.x, gw = blockIdx.x * 8 + wave, NGW = G * 8;
;     bf16_t* Win_t = (bf16_t*)(P.ws + WS_WIN); bf16_t* Wout_t = (bf16_t*)(P.ws + WS_WOUT); bf16_t* H = (bf16_t*)(P.ws + WS_H);
;     LAS float* wfL = (LAS float*)(lds + 69632);
;     for (int i = tid; i < 1024 * 8; i += 512) wfL[i] = P.win[(size_t)(i >> 3) * DIN + 4096 + (i & 7)];
;     LAS float* scr = (LAS float*)(lds + wave * 8704);
;     for (int it = gw; it < 2048 + 512; it += NGW) {
;         if (it < 2048) p0_transpose_item(P.win, DIN, 4096, 1024, Win_t, scr, it, lane);
;         else p0_transpose_item(P.wout, 1024, 1024, 1024, Wout_t, scr, it - 2048, lane);
;     }
.LBB0_5:
	s_or_b64 exec, exec, s[2:3]
	v_mov_b32_e32 v178, v184
	s_movk_i32 s2, 0x2000
	s_nop 0
	v_and_b32_e32 v19, 7, v178
	v_lshrrev_b32_e32 v1, 3, v178
	v_mul_u32_u24_e32 v1, 0x4020, v1
	v_lshl_add_u32 v1, v19, 2, v1
	v_add_u32_e32 v1, 0x4000, v1
	s_mov_b64 s[4:5], s[36:37]
	global_load_dword v20, v1, s[4:5]
	s_add_u32 s4, s4, 0x100800
	s_addc_u32 s5, s5, 0
	global_load_dword v21, v1, s[4:5]
	s_add_u32 s4, s4, 0x100800
	s_addc_u32 s5, s5, 0
	global_load_dword v22, v1, s[4:5]
	s_add_u32 s4, s4, 0x100800
	s_addc_u32 s5, s5, 0
	global_load_dword v23, v1, s[4:5]
	s_add_u32 s4, s4, 0x100800
	s_addc_u32 s5, s5, 0
	global_load_dword v24, v1, s[4:5]
	s_add_u32 s4, s4, 0x100800
	s_addc_u32 s5, s5, 0
	global_load_dword v25, v1, s[4:5]
	s_add_u32 s4, s4, 0x100800
	s_addc_u32 s5, s5, 0
	global_load_dword v26, v1, s[4:5]
	s_add_u32 s4, s4, 0x100800
	s_addc_u32 s5, s5, 0
	global_load_dword v27, v1, s[4:5]
	s_add_u32 s4, s4, 0x100800
	s_addc_u32 s5, s5, 0
	global_load_dword v28, v1, s[4:5]
	s_add_u32 s4, s4, 0x100800
	s_addc_u32 s5, s5, 0
	global_load_dword v29, v1, s[4:5]
	s_add_u32 s4, s4, 0x100800
	s_addc_u32 s5, s5, 0
	global_load_dword v30, v1, s[4:5]
	s_add_u32 s4, s4, 0x100800
	s_addc_u32 s5, s5, 0
	global_load_dword v31, v1, s[4:5]
	s_add_u32 s4, s4, 0x100800
	s_addc_u32 s5, s5, 0
	global_load_dword v32, v1, s[4:5]
	s_add_u32 s4, s4, 0x100800
	s_addc_u32 s5, s5, 0
	global_load_dword v33, v1, s[4:5]
	s_add_u32 s4, s4, 0x100800
	s_addc_u32 s5, s5, 0
	global_load_dword v34, v1, s[4:5]
	s_add_u32 s4, s4, 0x100800
	s_addc_u32 s5, s5, 0
	global_load_dword v35, v1, s[4:5]
	v_lshl_add_u32 v2, v178, 2, 0
	v_add_u32_e32 v2, 0x11000, v2
	s_waitcnt vmcnt(15)
	ds_write_b32 v2, v20
	s_waitcnt vmcnt(14)
	ds_write_b32 v2, v21 offset:2048
	s_waitcnt vmcnt(13)
	ds_write_b32 v2, v22 offset:4096
	s_waitcnt vmcnt(12)
	ds_write_b32 v2, v23 offset:6144
	s_waitcnt vmcnt(11)
	ds_write_b32 v2, v24 offset:8192
	s_waitcnt vmcnt(10)
	ds_write_b32 v2, v25 offset:10240
	s_waitcnt vmcnt(9)
	ds_write_b32 v2, v26 offset:12288
	s_waitcnt vmcnt(8)
	ds_write_b32 v2, v27 offset:14336
	s_waitcnt vmcnt(7)
	ds_write_b32 v2, v28 offset:16384
	s_waitcnt vmcnt(6)
	ds_write_b32 v2, v29 offset:18432
	s_waitcnt vmcnt(5)
	ds_write_b32 v2, v30 offset:20480
	s_waitcnt vmcnt(4)
	ds_write_b32 v2, v31 offset:22528
	s_waitcnt vmcnt(3)
	ds_write_b32 v2, v32 offset:24576
	s_waitcnt vmcnt(2)
	ds_write_b32 v2, v33 offset:26624
	s_waitcnt vmcnt(1)
	ds_write_b32 v2, v34 offset:28672
	s_waitcnt vmcnt(0)
	ds_write_b32 v2, v35 offset:30720
	s_load_dwordx16 s[68:83], s[0:1], 0x0
	s_lshr_b32 s86, s16, 6
	s_lshl_b32 s0, s13, 3
	s_add_i32 s2, s86, s0
	s_lshl_b32 s84, s94, 3
	v_writelane_b32 v241, s16, 6
	s_add_u32 s0, s92, 0x800000
	v_writelane_b32 v241, s13, 7
	s_addc_u32 s1, s93, 0
	v_writelane_b32 v241, s0, 8
	v_and_b32_e32 v146, 63, v178
	s_cmpk_gt_i32 s2, 0x9ff
	v_writelane_b32 v241, s1, 9
	s_mov_b32 s0, s2
	v_writelane_b32 v241, s0, 10
	s_mul_i32 s2, s86, 0x2200
	s_nop 0
	v_writelane_b32 v241, s1, 11
	s_cbranch_scc1 .LBB0_28
	v_lshlrev_b32_e32 v1, 2, v178
	v_and_b32_e32 v14, 0x7c, v1
	v_lshlrev_b32_e32 v1, 3, v146
	v_and_b32_e32 v1, 56, v1
	v_readlane_b32 s4, v241, 8
	v_lshrrev_b32_e32 v5, 3, v146
	v_lshlrev_b32_e32 v6, 1, v1
	v_mov_b32_e32 v7, 0
	v_readlane_b32 s5, v241, 9
	s_add_i32 s0, s2, 0
	v_lshrrev_b32_e32 v2, 5, v146
	v_mul_u32_u24_e32 v3, 0x84, v1
	v_lshl_add_u64 v[8:9], s[4:5], 0, v[6:7]
	v_lshlrev_b32_e32 v1, 2, v5
	v_mov_b32_e32 v15, v7
	v_readlane_b32 s4, v241, 10
	s_mov_b32 s1, 0
	v_add_u32_e32 v4, s0, v14
	s_movk_i32 s3, 0x84
	v_add3_u32 v20, s0, v3, v1
	v_or_b32_e32 v21, 8, v5
	v_or_b32_e32 v22, 16, v5
	v_or_b32_e32 v23, 24, v5
	v_lshl_add_u64 v[10:11], s[92:93], 0, v[6:7]
	v_lshl_add_u64 v[12:13], s[42:43], 0, v[14:15]
	v_lshl_add_u64 v[14:15], s[36:37], 0, v[14:15]
	v_mov_b32_e32 v1, v2
	s_movk_i32 s8, 0x4020
	s_mov_b32 s9, s4
	v_readlane_b32 s5, v241, 11
	s_branch .LBB0_20

; template <class F>
; __device__ __forceinline__ void mini_gemm64(const bf16_t* __restrict__ A, const bf16_t* __restrict__ Bt, int wave, int lane, F&& epi) {
;     const int fr = lane & 15, fq = lane >> 4;
;     const bf16_t* ap = A + (size_t)(16 * (wave >> 1) + fr) * 1024 + 8 * fq;
;     const bf16_t* b0 = Bt + (size_t)(32 * (wave & 1) + fr) * 1024 + 8 * fq;
;     const bf16_t* b1 = b0 + 16 * 1024;
;     f32x4 acc0 = {0.f, 0.f, 0.f, 0.f}, acc1 = {0.f, 0.f, 0.f, 0.f};
; #pragma unroll 8
;     for (int ks = 0; ks < 32; ++ks) {
;         const bf16x8 a = *(const bf16x8*)(ap + ks * 32), x0 = *(const bf16x8*)(b0 + ks * 32), x1 = *(const bf16x8*)(b1 + ks * 32);
;         acc0 = __builtin_amdgcn_mfma_f32_16x16x32_bf16(x0, a, acc0, 0, 0, 0);
;         acc1 = __builtin_amdgcn_mfma_f32_16x16x32_bf16(x1, a, acc1, 0, 0, 0);
;     }
.LBB0_187:
	v_add_co_u32_e32 v56, vcc, 0x8000, v10
	s_nop 1
	v_addc_co_u32_e32 v57, vcc, 0, v11, vcc
	global_load_dwordx4 v[60:63], v[8:9], off offset:-256
	global_load_dwordx4 v[64:67], v[10:11], off
	global_load_dwordx4 v[68:71], v[56:57], off
	global_load_dwordx4 v[72:75], v[8:9], off offset:-192
	global_load_dwordx4 v[76:79], v[10:11], off offset:64
	global_load_dwordx4 v[80:83], v[56:57], off offset:64
	global_load_dwordx4 v[84:87], v[8:9], off offset:-128
	global_load_dwordx4 v[88:91], v[10:11], off offset:128
	global_load_dwordx4 v[92:95], v[56:57], off offset:128
	global_load_dwordx4 v[96:99], v[8:9], off offset:-64
	global_load_dwordx4 v[100:103], v[10:11], off offset:192
	global_load_dwordx4 v[104:107], v[56:57], off offset:192
	global_load_dwordx4 v[108:111], v[8:9], off
	global_load_dwordx4 v[112:115], v[10:11], off offset:256
	global_load_dwordx4 v[116:119], v[56:57], off offset:256
	global_load_dwordx4 v[120:123], v[8:9], off offset:64
	global_load_dwordx4 v[124:127], v[10:11], off offset:320
	global_load_dwordx4 v[128:131], v[56:57], off offset:320
	global_load_dwordx4 v[132:135], v[8:9], off offset:128
	global_load_dwordx4 v[136:139], v[10:11], off offset:384
	global_load_dwordx4 v[140:143], v[56:57], off offset:384
	global_load_dwordx4 v[144:147], v[8:9], off offset:192
	global_load_dwordx4 v[148:151], v[10:11], off offset:448
	global_load_dwordx4 v[152:155], v[56:57], off offset:448
	global_load_dwordx4 v[160:163], v[8:9], off offset:256
	global_load_dwordx4 v[164:167], v[10:11], off offset:512
	global_load_dwordx4 v[168:171], v[56:57], off offset:512
	global_load_dwordx4 v[172:175], v[8:9], off offset:320
	global_load_dwordx4 v[180:183], v[10:11], off offset:576
	global_load_dwordx4 v[186:189], v[56:57], off offset:576
	global_load_dwordx4 v[190:193], v[8:9], off offset:384
	global_load_dwordx4 v[194:197], v[10:11], off offset:640
	global_load_dwordx4 v[198:201], v[56:57], off offset:640
	global_load_dwordx4 v[202:205], v[8:9], off offset:448
	global_load_dwordx4 v[206:209], v[10:11], off offset:704
	global_load_dwordx4 v[210:213], v[56:57], off offset:704
	global_load_dwordx4 v[214:217], v[8:9], off offset:512
	global_load_dwordx4 v[218:221], v[10:11], off offset:768
	global_load_dwordx4 v[222:225], v[56:57], off offset:768
	global_load_dwordx4 v[226:229], v[8:9], off offset:576
	global_load_dwordx4 v[230:233], v[10:11], off offset:832
	global_load_dwordx4 v[234:237], v[56:57], off offset:832
	s_waitcnt vmcnt(39)
	v_mfma_f32_16x16x32_bf16 v[4:7], v[64:67], v[60:63], v[4:7]
	v_mfma_f32_16x16x32_bf16 v[0:3], v[68:71], v[60:63], v[0:3]
	global_load_dwordx4 v[60:63], v[8:9], off offset:640
	global_load_dwordx4 v[64:67], v[10:11], off offset:896
	global_load_dwordx4 v[68:71], v[56:57], off offset:896
	s_waitcnt vmcnt(39)
	v_mfma_f32_16x16x32_bf16 v[4:7], v[76:79], v[72:75], v[4:7]
	v_mfma_f32_16x16x32_bf16 v[0:3], v[80:83], v[72:75], v[0:3]
	global_load_dwordx4 v[72:75], v[8:9], off offset:704
	global_load_dwordx4 v[76:79], v[10:11], off offset:960
	global_load_dwordx4 v[80:83], v[56:57], off offset:960
	s_waitcnt vmcnt(39)
	v_mfma_f32_16x16x32_bf16 v[4:7], v[88:91], v[84:87], v[4:7]
	v_mfma_f32_16x16x32_bf16 v[0:3], v[92:95], v[84:87], v[0:3]
	global_load_dwordx4 v[84:87], v[8:9], off offset:768
	global_load_dwordx4 v[88:91], v[10:11], off offset:1024
	global_load_dwordx4 v[92:95], v[56:57], off offset:1024
	s_waitcnt vmcnt(39)
	v_mfma_f32_16x16x32_bf16 v[4:7], v[100:103], v[96:99], v[4:7]
	v_mfma_f32_16x16x32_bf16 v[0:3], v[104:107], v[96:99], v[0:3]
	global_load_dwordx4 v[96:99], v[8:9], off offset:832
	global_load_dwordx4 v[100:103], v[10:11], off offset:1088
	global_load_dwordx4 v[104:107], v[56:57], off offset:1088
	s_waitcnt vmcnt(39)
	v_mfma_f32_16x16x32_bf16 v[4:7], v[112:115], v[108:111], v[4:7]
	v_mfma_f32_16x16x32_bf16 v[0:3], v[116:119], v[108:111], v[0:3]
	global_load_dwordx4 v[108:111], v[8:9], off offset:896
	global_load_dwordx4 v[112:115], v[10:11], off offset:1152
	global_load_dwordx4 v[116:119], v[56:57], off offset:1152
	s_waitcnt vmcnt(39)
	v_mfma_f32_16x16x32_bf16 v[4:7], v[124:127], v[120:123], v[4:7]
	v_mfma_f32_16x16x32_bf16 v[0:3], v[128:131], v[120:123], v[0:3]
	global_load_dwordx4 v[120:123], v[8:9], off offset:960
	global_load_dwordx4 v[124:127], v[10:11], off offset:1216
	global_load_dwordx4 v[128:131], v[56:57], off offset:1216
	s_waitcnt vmcnt(39)
	v_mfma_f32_16x16x32_bf16 v[4:7], v[136:139], v[132:135], v[4:7]
	v_mfma_f32_16x16x32_bf16 v[0:3], v[140:143], v[132:135], v[0:3]
	global_load_dwordx4 v[132:135], v[8:9], off offset:1024
	global_load_dwordx4 v[136:139], v[10:11], off offset:1280
	global_load_dwordx4 v[140:143], v[56:57], off offset:1280
	s_waitcnt vmcnt(39)
	v_mfma_f32_16x16x32_bf16 v[4:7], v[148:151], v[144:147], v[4:7]
	v_mfma_f32_16x16x32_bf16 v[0:3], v[152:155], v[144:147], v[0:3]
	global_load_dwordx4 v[144:147], v[8:9], off offset:1088
	global_load_dwordx4 v[148:151], v[10:11], off offset:1344
	global_load_dwordx4 v[152:155], v[56:57], off offset:1344
	s_waitcnt vmcnt(39)
	v_mfma_f32_16x16x32_bf16 v[4:7], v[164:167], v[160:163], v[4:7]
	v_mfma_f32_16x16x32_bf16 v[0:3], v[168:171], v[160:163], v[0:3]
	global_load_dwordx4 v[160:163], v[8:9], off offset:1152
	global_load_dwordx4 v[164:167], v[10:11], off offset:1408
	global_load_dwordx4 v[168:171], v[56:57], off offset:1408
	s_waitcnt vmcnt(39)
; template <class F>
; __device__ __forceinline__ void mini_gemm64(const bf16_t* __restrict__ A, const bf16_t* __restrict__ Bt, int wave, int lane, F&& epi) {
;     ...
;     for (int ks = 0; ks < 32; ++ks) {
;         const bf16x8 a = *(const bf16x8*)(ap + ks * 32), x0 = *(const bf16x8*)(b0 + ks * 32), x1 = *(const bf16x8*)(b1 + ks * 32);
;         acc0 = __builtin_amdgcn_mfma_f32_16x16x32_bf16(x0, a, acc0, 0, 0, 0);
;         acc1 = __builtin_amdgcn_mfma_f32_16x16x32_bf16(x1, a, acc1, 0, 0, 0);
;     }
;     const int row = 16 * (wave >> 1) + fr, col = 32 * (wave & 1) + 4 * fq;
;     epi(row, col, acc0); epi(row, col + 16, acc1);
; __global__ void __launch_bounds__(512, 2) hymba_fwd(Params Parg) {
;     ...
;                 [&](int row, int col, f32x4 v) {
;                     const int r = rg * 64 + row;
;                     if (fdst) *(f32x4*)(fdst + (size_t)r * 512 + head * 64 + col) = v;
	v_mfma_f32_16x16x32_bf16 v[4:7], v[180:183], v[172:175], v[4:7]
	v_mfma_f32_16x16x32_bf16 v[0:3], v[186:189], v[172:175], v[0:3]
	global_load_dwordx4 v[172:175], v[8:9], off offset:1216
	global_load_dwordx4 v[180:183], v[10:11], off offset:1472
	global_load_dwordx4 v[186:189], v[56:57], off offset:1472
	s_waitcnt vmcnt(39)
	v_mfma_f32_16x16x32_bf16 v[4:7], v[194:197], v[190:193], v[4:7]
	v_mfma_f32_16x16x32_bf16 v[0:3], v[198:201], v[190:193], v[0:3]
	global_load_dwordx4 v[190:193], v[8:9], off offset:1280
	global_load_dwordx4 v[194:197], v[10:11], off offset:1536
	global_load_dwordx4 v[198:201], v[56:57], off offset:1536
	s_waitcnt vmcnt(39)
	v_mfma_f32_16x16x32_bf16 v[4:7], v[206:209], v[202:205], v[4:7]
	v_mfma_f32_16x16x32_bf16 v[0:3], v[210:213], v[202:205], v[0:3]
	global_load_dwordx4 v[202:205], v[8:9], off offset:1344
	global_load_dwordx4 v[206:209], v[10:11], off offset:1600
	global_load_dwordx4 v[210:213], v[56:57], off offset:1600
	s_waitcnt vmcnt(39)
	v_mfma_f32_16x16x32_bf16 v[4:7], v[218:221], v[214:217], v[4:7]
	v_mfma_f32_16x16x32_bf16 v[0:3], v[222:225], v[214:217], v[0:3]
	global_load_dwordx4 v[214:217], v[8:9], off offset:1408
	global_load_dwordx4 v[218:221], v[10:11], off offset:1664
	global_load_dwordx4 v[222:225], v[56:57], off offset:1664
	s_waitcnt vmcnt(39)
	v_mfma_f32_16x16x32_bf16 v[4:7], v[230:233], v[226:229], v[4:7]
	v_mfma_f32_16x16x32_bf16 v[0:3], v[234:237], v[226:229], v[0:3]
	global_load_dwordx4 v[226:229], v[8:9], off offset:1472
	global_load_dwordx4 v[230:233], v[10:11], off offset:1728
	global_load_dwordx4 v[234:237], v[56:57], off offset:1728
	s_waitcnt vmcnt(39)
	v_mfma_f32_16x16x32_bf16 v[4:7], v[64:67], v[60:63], v[4:7]
	v_mfma_f32_16x16x32_bf16 v[0:3], v[68:71], v[60:63], v[0:3]
	global_load_dwordx4 v[60:63], v[8:9], off offset:1536
	global_load_dwordx4 v[64:67], v[10:11], off offset:1792
	global_load_dwordx4 v[68:71], v[56:57], off offset:1792
	s_waitcnt vmcnt(39)
	v_mfma_f32_16x16x32_bf16 v[4:7], v[76:79], v[72:75], v[4:7]
	v_mfma_f32_16x16x32_bf16 v[0:3], v[80:83], v[72:75], v[0:3]
	global_load_dwordx4 v[72:75], v[8:9], off offset:1600
	global_load_dwordx4 v[76:79], v[10:11], off offset:1856
	global_load_dwordx4 v[80:83], v[56:57], off offset:1856
	s_waitcnt vmcnt(39)
	v_mfma_f32_16x16x32_bf16 v[4:7], v[88:91], v[84:87], v[4:7]
	v_mfma_f32_16x16x32_bf16 v[0:3], v[92:95], v[84:87], v[0:3]
	global_load_dwordx4 v[84:87], v[8:9], off offset:1664
	global_load_dwordx4 v[88:91], v[10:11], off offset:1920
	global_load_dwordx4 v[92:95], v[56:57], off offset:1920
	s_waitcnt vmcnt(39)
	v_mfma_f32_16x16x32_bf16 v[4:7], v[100:103], v[96:99], v[4:7]
	v_mfma_f32_16x16x32_bf16 v[0:3], v[104:107], v[96:99], v[0:3]
	global_load_dwordx4 v[96:99], v[8:9], off offset:1728
	global_load_dwordx4 v[100:103], v[10:11], off offset:1984
	global_load_dwordx4 v[104:107], v[56:57], off offset:1984
	s_waitcnt vmcnt(39)
	v_mfma_f32_16x16x32_bf16 v[4:7], v[112:115], v[108:111], v[4:7]
	v_mfma_f32_16x16x32_bf16 v[0:3], v[116:119], v[108:111], v[0:3]
	s_waitcnt vmcnt(36)
	v_mfma_f32_16x16x32_bf16 v[4:7], v[124:127], v[120:123], v[4:7]
	v_mfma_f32_16x16x32_bf16 v[0:3], v[128:131], v[120:123], v[0:3]
	s_waitcnt vmcnt(33)
	v_mfma_f32_16x16x32_bf16 v[4:7], v[136:139], v[132:135], v[4:7]
	v_mfma_f32_16x16x32_bf16 v[0:3], v[140:143], v[132:135], v[0:3]
	s_waitcnt vmcnt(30)
	v_mfma_f32_16x16x32_bf16 v[4:7], v[148:151], v[144:147], v[4:7]
	v_mfma_f32_16x16x32_bf16 v[0:3], v[152:155], v[144:147], v[0:3]
	s_waitcnt vmcnt(27)
	v_mfma_f32_16x16x32_bf16 v[4:7], v[164:167], v[160:163], v[4:7]
	v_mfma_f32_16x16x32_bf16 v[0:3], v[168:171], v[160:163], v[0:3]
	s_waitcnt vmcnt(24)
	v_mfma_f32_16x16x32_bf16 v[4:7], v[180:183], v[172:175], v[4:7]
	v_mfma_f32_16x16x32_bf16 v[0:3], v[186:189], v[172:175], v[0:3]
	s_waitcnt vmcnt(21)
	v_mfma_f32_16x16x32_bf16 v[4:7], v[194:197], v[190:193], v[4:7]
	v_mfma_f32_16x16x32_bf16 v[0:3], v[198:201], v[190:193], v[0:3]
	s_waitcnt vmcnt(18)
	v_mfma_f32_16x16x32_bf16 v[4:7], v[206:209], v[202:205], v[4:7]
	v_mfma_f32_16x16x32_bf16 v[0:3], v[210:213], v[202:205], v[0:3]
	s_waitcnt vmcnt(15)
	v_mfma_f32_16x16x32_bf16 v[4:7], v[218:221], v[214:217], v[4:7]
	v_mfma_f32_16x16x32_bf16 v[0:3], v[222:225], v[214:217], v[0:3]
	s_waitcnt vmcnt(12)
	v_mfma_f32_16x16x32_bf16 v[4:7], v[230:233], v[226:229], v[4:7]
	v_mfma_f32_16x16x32_bf16 v[0:3], v[234:237], v[226:229], v[0:3]
	s_waitcnt vmcnt(9)
	v_mfma_f32_16x16x32_bf16 v[4:7], v[64:67], v[60:63], v[4:7]
	v_mfma_f32_16x16x32_bf16 v[0:3], v[68:71], v[60:63], v[0:3]
	s_waitcnt vmcnt(6)
	v_mfma_f32_16x16x32_bf16 v[4:7], v[76:79], v[72:75], v[4:7]
	v_mfma_f32_16x16x32_bf16 v[0:3], v[80:83], v[72:75], v[0:3]
	s_waitcnt vmcnt(3)
	v_mfma_f32_16x16x32_bf16 v[4:7], v[88:91], v[84:87], v[4:7]
	v_mfma_f32_16x16x32_bf16 v[0:3], v[92:95], v[84:87], v[0:3]
	s_waitcnt vmcnt(0)
	v_mfma_f32_16x16x32_bf16 v[4:7], v[100:103], v[96:99], v[4:7]
	v_mfma_f32_16x16x32_bf16 v[0:3], v[104:107], v[96:99], v[0:3]
	s_nop 7
	s_mov_b64 s[18:19], 0x800
	s_lshl_b32 s0, s28, 6
	s_and_b32 s0, s0, 0xc0
	s_and_b32 s11, s16, 7
	s_cmp_lg_u64 s[14:15], 0
	v_add_u32_e32 v24, s0, v12
	s_cselect_b64 s[16:17], -1, 0
	s_cmp_eq_u64 s[14:15], 0
	v_lshlrev_b32_e32 v26, 2, v18
	s_cbranch_scc1 .LBB0_190
	v_mov_b32_e32 v25, v15
	v_lshlrev_b64 v[8:9], 11, v[24:25]
	v_lshl_add_u64 v[8:9], s[14:15], 0, v[8:9]
	s_lshl_b32 s0, s11, 8
	v_lshl_add_u64 v[8:9], v[8:9], 0, s[0:1]
	v_mov_b32_e32 v27, v15
	v_lshl_add_u64 v[8:9], v[8:9], 0, v[26:27]
	global_store_dwordx4 v[8:9], v[4:7], off

; #define LAS __attribute__((address_space(3)))
; __device__ __forceinline__ void phase2(const Params& P, LAS unsigned char* lds, int tid, int lane, int wave) {
;     LAS float* c2p = (LAS float*)(lds);
;     LAS float* c2s = (LAS float*)(lds + 8192);
;     LAS float* rb2 = (LAS float*)(lds + 8192 + 8448);
;     LAS unsigned char* work = lds + 18432;
;     for (int vb = blockIdx.x; vb < 256; vb += gridDim.x) {
;         const int b = vb >> 3, h = vb & 7;
;         __syncthreads();
;         {
;             const float* C2P = (const float*)(P.ws + WS_C2P); const float* C2S = (const float*)(P.ws + WS_C2S);
;             for (int i = tid; i < 2048; i += 512) c2p[i] = C2P[(size_t)vb * 2048 + i];
;             if (vb < 64) for (int i = tid; i < LBS_LEN; i += 512) c2s[i] = C2S[(size_t)vb * LBS_LEN + i];
;             for (int i = tid; i < NREL; i += 512) rb2[i] = P.relb[h * NREL + i] * LOG2E;
;         }
;         __syncthreads();
;         if (vb < 128) {
;             const int mode = vb < 64, bs = (vb & 63) >> 3;
;             const size_t qrow = (size_t)MP + bs * NST;
;             const int L = mode ? LBS_LEN : LAS_LEN, nb = L / 32;
;             const size_t kvo = (size_t)(bs * 8 + h) * L * 64;
;             const size_t qgo = ((size_t)(32 * 8 + h) * 2048 + bs * NST) * 64;
;             const int kb0 = (wave * nb) >> 3, kb1 = ((wave + 1) * nb) >> 3;
;             const bf16_t* Qrow = (const bf16_t*)(P.ws + WS_SEG + (size_t)(mode ? 4 : 0) * SEG_STRIDE) + qgo;
;             const bf16_t* Grow = (const bf16_t*)(P.ws + WS_SEG + (size_t)(mode ? 7 : 3) * SEG_STRIDE) + qgo;
;             bf16_t* Yrow = (bf16_t*)(P.ws + WS_H) + qrow * 1024 + (mode ? 512 : 0) + h * 64;
;             if (mode) att::split_unit<1>(Qrow, (const bf16_t*)(P.ws + WS_KBS) + kvo, (const bf16_t*)(P.ws + WS_VBS) + kvo, kb0, kb1, nb - 1, PAST, c2s, Yrow, Grow, work, wave, lane);
;             else      att::split_unit<0>(Qrow, (const bf16_t*)(P.ws + WS_KAS) + kvo, (const bf16_t*)(P.ws + WS_VAS) + kvo, kb0, kb1, -1, LAC, rb2, Yrow, Grow, work, wave, lane);
.LBB0_497:
	s_or_b64 exec, exec, s[0:1]
	v_mov_b32_e32 v120, v184
	s_andn2_b64 vcc, exec, s[40:41]
	s_waitcnt lgkmcnt(0)
	s_barrier
	s_cmp_ge_u32 s86, 4
	s_cbranch_scc0 .Lp2_noprio
	s_setprio 1
.Lp2_noprio:
	s_cbranch_vccnz .LBB0_657
	s_movk_i32 s0, 0x800
	s_movk_i32 s4, 0x800
	v_writelane_b32 v241, s0, 24
	v_max_i32_e32 v6, 0x600, v120
	v_sub_u32_e32 v6, v6, v120
	v_writelane_b32 v241, s1, 25
	v_cmp_gt_i32_e64 s[0:1], s4, v120
	v_add_u32_e32 v6, 0x1ff, v6
	v_lshrrev_b32_e32 v7, 9, v6
	v_writelane_b32 v241, s0, 26
	v_add_u32_e32 v8, 1, v7
	v_add_u32_e32 v7, -1, v7
	v_writelane_b32 v241, s1, 27
	s_movk_i32 s0, 0x81f
	v_cmp_lt_i32_e64 s[0:1], s0, v120
	v_lshrrev_b32_e32 v9, 1, v7
	v_add_u32_e32 v9, 1, v9
	v_writelane_b32 v241, s0, 28
	v_and_b32_e32 v128, 7, v9
	v_max_i32_e32 v3, 0x620, v120
	v_writelane_b32 v241, s1, 29
	s_movk_i32 s0, 0x101
	v_cmp_gt_i32_e64 s[0:1], s0, v120
	v_sub_u32_e32 v3, v3, v120
	v_add_u32_e32 v3, 0x1ff, v3
	v_writelane_b32 v241, s0, 30
	v_lshrrev_b32_e32 v4, 9, v3
	v_add_u32_e32 v5, 1, v4
	v_writelane_b32 v241, s1, 31
	s_add_i32 s0, s2, 0
	v_writelane_b32 v241, s0, 32
	s_addk_i32 s0, 0x5800
	v_writelane_b32 v241, s0, 33
	v_add_u32_e32 v4, -1, v4
	v_readlane_b32 s1, v241, 6
	s_bfe_u32 s0, s1, 0x10006
	s_lshr_b32 s1, s1, 7
	s_lshl_b32 s2, s1, 10
	s_lshl_b32 s3, s0, 12
	s_add_i32 s2, s2, 0
	s_add_i32 s2, s2, s3
	s_add_i32 s3, s2, 0x11400
	v_writelane_b32 v241, s3, 34
	v_writelane_b32 v241, s2, 35
	s_add_i32 s2, s2, 0x13600
	s_lshl_b32 s0, s0, 5
	s_lshl_b32 s1, s1, 3
	v_writelane_b32 v241, s2, 36
	s_add_i32 s0, s0, s1
	v_writelane_b32 v241, s0, 37
	s_add_u32 s0, s92, 0xc00000
	v_writelane_b32 v241, s0, 38
	s_addc_u32 s0, s93, 0
	v_writelane_b32 v241, s0, 39
	s_add_u32 s0, s92, 0xa00000
	v_writelane_b32 v241, s0, 40
	s_addc_u32 s0, s93, 0
	v_writelane_b32 v241, s0, 41
	s_add_u32 s0, s92, 0xc800000
	v_writelane_b32 v241, s0, 42
	s_addc_u32 s0, s93, 0
	v_writelane_b32 v241, s0, 43
	s_add_u32 s0, s92, 0x1c00000
	v_writelane_b32 v241, s0, 44
	s_addc_u32 s0, s93, 0
	v_writelane_b32 v241, s0, 45
	s_add_u32 s0, s92, 0x2d00000
	v_writelane_b32 v241, s0, 46
	s_addc_u32 s0, s93, 0
	v_writelane_b32 v241, s0, 47
	s_add_u32 s0, s92, 0x1200000
	v_writelane_b32 v241, s0, 48
	s_addc_u32 s0, s93, 0
	v_writelane_b32 v241, s0, 49
	s_add_u32 s0, s92, 0x1700000
	v_writelane_b32 v241, s0, 50
	s_addc_u32 s0, s93, 0
	v_writelane_b32 v241, s0, 51
	s_movk_i32 s0, 0x1ff
	v_cmp_lt_u32_e64 s[2:3], s0, v6
	v_and_b32_e32 v6, 0xfffffe, v8
	v_lshrrev_b32_e32 v10, 1, v4
	v_writelane_b32 v241, s2, 52
	v_add_u32_e32 v10, 1, v10
	v_and_b32_e32 v131, 7, v10
	v_writelane_b32 v241, s3, 53
	v_cmp_lt_u32_e64 s[2:3], 13, v7
	v_max_i32_e32 v0, 0xffffff01, v120
	v_sub_u32_e32 v0, v0, v120
	v_writelane_b32 v241, s2, 54
	v_add_u32_e32 v0, 0x1ff, v0
	v_lshrrev_b32_e32 v1, 9, v0
	v_writelane_b32 v241, s3, 55
	v_cmp_ne_u32_e64 s[2:3], 0, v128
	v_add_u32_e32 v2, 1, v1
	v_add_u32_e32 v1, -1, v1
	v_writelane_b32 v241, s2, 56
	v_lshrrev_b32_e32 v11, 1, v1
	v_add_u32_e32 v11, 1, v11
	v_writelane_b32 v241, s3, 57
	v_cmp_ne_u32_e64 s[2:3], v8, v6
	v_and_b32_e32 v134, 3, v11
	v_lshlrev_b32_e32 v136, 2, v120
	v_writelane_b32 v241, s2, 58
	v_add_u32_e32 v137, 0, v136
	s_movk_i32 s26, 0xe000
	v_writelane_b32 v241, s3, 59
	v_cmp_lt_u32_e64 s[2:3], s0, v3
	v_and_b32_e32 v3, 0xfffffe, v5
	v_cmp_lt_u32_e64 s[0:1], s0, v0
	v_writelane_b32 v241, s2, 60
	v_and_b32_e32 v0, 0xfffffe, v2
	v_and_b32_e32 v126, 63, v120
	v_writelane_b32 v241, s3, 61
	v_cmp_lt_u32_e64 s[2:3], 13, v4
	s_mov_b32 s13, 0
	v_lshl_add_u32 v127, v6, 9, v120
	v_writelane_b32 v241, s2, 62
	v_add_u32_e32 v121, 0x200, v120
	v_and_b32_e32 v129, -8, v9
	v_writelane_b32 v241, s3, 63
	v_cmp_ne_u32_e64 s[2:3], 0, v131
	v_lshl_add_u32 v130, v3, 9, v120
	v_and_b32_e32 v132, -8, v10
	v_writelane_b32 v240, s2, 0
	v_lshl_add_u32 v133, v0, 9, v120
	v_and_b32_e32 v135, -4, v11
	v_writelane_b32 v240, s3, 1
	v_cmp_ne_u32_e64 s[2:3], v5, v3
	v_add_u32_e32 v138, 0x2000, v137
	v_add_u32_e32 v139, 0x4100, v137
	v_writelane_b32 v240, s2, 2
	s_mov_b64 s[28:29], 0x800
	s_mov_b32 s36, 0x3fb8aa3b
	v_writelane_b32 v240, s3, 3
	v_writelane_b32 v240, s0, 4
	s_mov_b32 s33, 0xc600000
	s_mov_b64 s[66:67], 0x2000
	v_writelane_b32 v240, s1, 5
	v_cmp_lt_u32_e64 s[0:1], 5, v1
	v_mov_b32_e32 v1, 0
	s_mov_b32 s27, -1
	v_writelane_b32 v240, s0, 6
	v_mov_b32_e32 v140, 0xf149f2ca
	v_mov_b32_e32 v141, 0x100
	v_writelane_b32 v240, s1, 7
	v_cmp_ne_u32_e64 s[0:1], 0, v134
	s_nop 1
	v_writelane_b32 v240, s0, 8
	s_nop 1
	v_writelane_b32 v240, s1, 9
	v_cmp_ne_u32_e64 s[0:1], v2, v0
	s_nop 1
	v_writelane_b32 v240, s0, 10
	s_nop 1
	v_writelane_b32 v240, s1, 11
	s_lshl_b32 s0, s86, 5
	s_sub_i32 s0, s0, 63
	v_writelane_b32 v240, s0, 12
	s_add_i32 s0, 0, 0x300
	v_writelane_b32 v240, s0, 13
	v_writelane_b32 v240, s68, 14
	v_readlane_b32 s0, v241, 7
	s_mov_b32 s37, s0
	v_writelane_b32 v240, s69, 15
	v_writelane_b32 v240, s70, 16
	v_writelane_b32 v240, s71, 17
	v_writelane_b32 v240, s72, 18
	v_writelane_b32 v240, s73, 19
	v_writelane_b32 v240, s74, 20
	v_writelane_b32 v240, s75, 21
	v_writelane_b32 v240, s76, 22
	v_writelane_b32 v240, s77, 23
	v_writelane_b32 v240, s78, 24
	v_writelane_b32 v240, s79, 25
	v_writelane_b32 v240, s80, 26
	v_writelane_b32 v240, s81, 27
	v_writelane_b32 v240, s82, 28
	v_writelane_b32 v240, s83, 29
	v_writelane_b32 v240, s84, 30
	s_mov_b32 s96, s0
	s_nop 0
	v_writelane_b32 v240, s85, 31
	v_writelane_b32 v240, s88, 32
	s_nop 1
	v_writelane_b32 v240, s89, 33
	v_writelane_b32 v240, s90, 34
	v_writelane_b32 v240, s91, 35
	v_writelane_b32 v240, s92, 36
	v_writelane_b32 v240, s93, 37
	v_writelane_b32 v240, s94, 38
	v_writelane_b32 v240, s95, 39
	v_writelane_b32 v240, s72, 40
	v_writelane_b32 v240, s73, 41
	s_branch .LBB0_500

; __device__ __forceinline__ unsigned xb_ld(unsigned* p)              { return __hip_atomic_load(p, __ATOMIC_RELAXED, __HIP_MEMORY_SCOPE_AGENT); }
; __device__ __forceinline__ void xcd_barrier_complete(unsigned* bar, unsigned x, unsigned& nloc, unsigned& nx) {
;     const unsigned G = gridDim.x * gridDim.y * gridDim.z;
;     unsigned sum, cnt, mine, sp = 0u;
;     for (;;) {
;         sum = 0u; cnt = 0u; mine = 0u;
; #pragma unroll
;         for (unsigned j = 0; j < 16; ++j) { const unsigned c = xb_ld(&bar[XB_XCNT(j)]); sum += c; cnt += (c > 0u) ? 1u : 0u; mine = (j == x) ? c : mine; }
; __device__ __forceinline__ void xcd_barrier(const XcdBarrier& b) {
;     asm volatile("s_waitcnt vmcnt(0)" ::: "memory");
;     __syncthreads();
;     if (threadIdx.x == 0) {
;         unsigned* bar = b.bar;
;         __builtin_amdgcn_s_waitcnt(0);
;         unsigned nloc = b.st[0], nx = b.st[1];
;         if (nloc == 0u) { xcd_barrier_complete(bar, b.x, nloc, nx); b.st[0] = nloc; b.st[1] = nx; }
.LBB0_657:
	s_setprio 0
	s_waitcnt vmcnt(0)
	s_barrier
	s_mov_b64 s[0:1], exec
	v_readlane_b32 s2, v241, 4
	v_readlane_b32 s3, v241, 5
	s_and_b64 s[2:3], s[0:1], s[2:3]
	s_mov_b64 exec, s[2:3]
	s_cbranch_execz .LBB0_709
	s_add_i32 s2, 0, 0x23fc0
	v_mov_b32_e32 v0, s2
	s_waitcnt vmcnt(0) expcnt(0) lgkmcnt(0)
	ds_read_b32 v2, v0
	s_add_i32 s2, 0, 0x23fc4
	v_mov_b32_e32 v0, s2
	ds_read_b32 v0, v0
	s_waitcnt lgkmcnt(1)
	v_cmp_ne_u32_e32 vcc, 0, v2
	s_cbranch_vccnz .LBB0_673
	s_add_u32 s4, s92, 0xd00200
	s_addc_u32 s5, s93, 0
	s_add_u32 s6, s92, 0xd00400
	s_addc_u32 s7, s93, 0
	s_add_u32 s8, s92, 0xd00500
	s_addc_u32 s9, s93, 0
	s_add_u32 s10, s92, 0xd00600
	s_addc_u32 s11, s93, 0
	s_add_u32 s12, s92, 0xd00700
	s_addc_u32 s13, s93, 0
	s_add_u32 s14, s92, 0xd00800
	s_addc_u32 s15, s93, 0
	s_add_u32 s16, s92, 0xd00900
	s_addc_u32 s17, s93, 0
	s_add_u32 s18, s92, 0xd00a00
	s_addc_u32 s19, s93, 0
	s_add_u32 s20, s92, 0xd00b00
	s_addc_u32 s21, s93, 0
	s_add_u32 s22, s92, 0xd00c00
	s_addc_u32 s23, s93, 0
	s_add_u32 s24, s92, 0xd00d00
	s_addc_u32 s25, s93, 0
	s_add_u32 s26, s92, 0xd00e00
	s_addc_u32 s27, s93, 0
	s_add_u32 s28, s92, 0xd00f00
	s_addc_u32 s29, s93, 0
	s_add_u32 s30, s92, 0xd01000
	s_addc_u32 s31, s93, 0
	s_add_u32 s34, s92, 0xd01100
	s_addc_u32 s35, s93, 0
	s_add_u32 s36, s92, 0xd01200
	v_readlane_b32 s2, v241, 0
	s_addc_u32 s37, s93, 0
	s_mul_i32 s2, s95, s2
	s_add_u32 s38, s92, 0xd01300
	s_mul_i32 s2, s2, s94
	s_addc_u32 s39, s93, 0
	s_mov_b32 s3, 1
	v_mov_b32_e32 v16, 0
	s_branch .LBB0_661

; template <class F>
; __device__ __forceinline__ void mini_gemm64(const bf16_t* __restrict__ A, const bf16_t* __restrict__ Bt, int wave, int lane, F&& epi) {
;     const int fr = lane & 15, fq = lane >> 4;
;     const bf16_t* ap = A + (size_t)(16 * (wave >> 1) + fr) * 1024 + 8 * fq;
;     const bf16_t* b0 = Bt + (size_t)(32 * (wave & 1) + fr) * 1024 + 8 * fq;
;     const bf16_t* b1 = b0 + 16 * 1024;
;     f32x4 acc0 = {0.f, 0.f, 0.f, 0.f}, acc1 = {0.f, 0.f, 0.f, 0.f};
; #pragma unroll 8
;     for (int ks = 0; ks < 32; ++ks) {
;         const bf16x8 a = *(const bf16x8*)(ap + ks * 32), x0 = *(const bf16x8*)(b0 + ks * 32), x1 = *(const bf16x8*)(b1 + ks * 32);
;         acc0 = __builtin_amdgcn_mfma_f32_16x16x32_bf16(x0, a, acc0, 0, 0, 0);
;         acc1 = __builtin_amdgcn_mfma_f32_16x16x32_bf16(x1, a, acc1, 0, 0, 0);
;     }
; __global__ void __launch_bounds__(512, 2) hymba_fwd(Params Parg) {
;     ...
;         for (int c = blockIdx.x; c < 64; c += gridDim.x) {
;             const int rg = c & 3, cg = c >> 2;
;             bf16_t* mo = (bf16_t*)(P.ws + WS_SEG);
;             mini_gemm64((const bf16_t*)(P.ws + WS_H) + (size_t)(MP + rg * 64) * 1024, (const bf16_t*)(P.ws + WS_WOUT) + (size_t)cg * 64 * 1024, wave, tid & 63,
.LBB0_714:
	v_add_co_u32_e32 v56, vcc, 0x800000, v18
	s_nop 1
	v_addc_co_u32_e32 v57, vcc, 0, v19, vcc
	v_add_co_u32_e32 v58, vcc, 0x808000, v18
	s_nop 1
	v_addc_co_u32_e32 v59, vcc, 0, v19, vcc
	global_load_dwordx4 v[60:63], v[16:17], off offset:-256
	global_load_dwordx4 v[64:67], v[56:57], off
	global_load_dwordx4 v[68:71], v[58:59], off
	global_load_dwordx4 v[72:75], v[16:17], off offset:-192
	global_load_dwordx4 v[76:79], v[56:57], off offset:64
	global_load_dwordx4 v[80:83], v[58:59], off offset:64
	global_load_dwordx4 v[84:87], v[16:17], off offset:-128
	global_load_dwordx4 v[88:91], v[56:57], off offset:128
	global_load_dwordx4 v[92:95], v[58:59], off offset:128
	global_load_dwordx4 v[96:99], v[16:17], off offset:-64
	global_load_dwordx4 v[100:103], v[56:57], off offset:192
	global_load_dwordx4 v[104:107], v[58:59], off offset:192
	global_load_dwordx4 v[108:111], v[16:17], off
	global_load_dwordx4 v[112:115], v[56:57], off offset:256
	global_load_dwordx4 v[116:119], v[58:59], off offset:256
	global_load_dwordx4 v[120:123], v[16:17], off offset:64
	global_load_dwordx4 v[124:127], v[56:57], off offset:320
	global_load_dwordx4 v[128:131], v[58:59], off offset:320
	global_load_dwordx4 v[132:135], v[16:17], off offset:128
	global_load_dwordx4 v[136:139], v[56:57], off offset:384
	global_load_dwordx4 v[140:143], v[58:59], off offset:384
	global_load_dwordx4 v[144:147], v[16:17], off offset:192
	global_load_dwordx4 v[148:151], v[56:57], off offset:448
	global_load_dwordx4 v[152:155], v[58:59], off offset:448
	global_load_dwordx4 v[160:163], v[16:17], off offset:256
	global_load_dwordx4 v[164:167], v[56:57], off offset:512
	global_load_dwordx4 v[168:171], v[58:59], off offset:512
	global_load_dwordx4 v[172:175], v[16:17], off offset:320
	global_load_dwordx4 v[180:183], v[56:57], off offset:576
	global_load_dwordx4 v[186:189], v[58:59], off offset:576
	global_load_dwordx4 v[190:193], v[16:17], off offset:384
	global_load_dwordx4 v[194:197], v[56:57], off offset:640
	global_load_dwordx4 v[198:201], v[58:59], off offset:640
	global_load_dwordx4 v[202:205], v[16:17], off offset:448
	global_load_dwordx4 v[206:209], v[56:57], off offset:704
	global_load_dwordx4 v[210:213], v[58:59], off offset:704
	global_load_dwordx4 v[214:217], v[16:17], off offset:512
	global_load_dwordx4 v[218:221], v[56:57], off offset:768
	global_load_dwordx4 v[222:225], v[58:59], off offset:768
	global_load_dwordx4 v[226:229], v[16:17], off offset:576
	global_load_dwordx4 v[230:233], v[56:57], off offset:832
	global_load_dwordx4 v[234:237], v[58:59], off offset:832
	s_waitcnt vmcnt(39)
	v_mfma_f32_16x16x32_bf16 v[4:7], v[64:67], v[60:63], v[4:7]
	v_mfma_f32_16x16x32_bf16 v[0:3], v[68:71], v[60:63], v[0:3]
	global_load_dwordx4 v[60:63], v[16:17], off offset:640
	global_load_dwordx4 v[64:67], v[56:57], off offset:896
	global_load_dwordx4 v[68:71], v[58:59], off offset:896
	s_waitcnt vmcnt(39)
	v_mfma_f32_16x16x32_bf16 v[4:7], v[76:79], v[72:75], v[4:7]
	v_mfma_f32_16x16x32_bf16 v[0:3], v[80:83], v[72:75], v[0:3]
	global_load_dwordx4 v[72:75], v[16:17], off offset:704
	global_load_dwordx4 v[76:79], v[56:57], off offset:960
	global_load_dwordx4 v[80:83], v[58:59], off offset:960
	s_waitcnt vmcnt(39)
	v_mfma_f32_16x16x32_bf16 v[4:7], v[88:91], v[84:87], v[4:7]
	v_mfma_f32_16x16x32_bf16 v[0:3], v[92:95], v[84:87], v[0:3]
	global_load_dwordx4 v[84:87], v[16:17], off offset:768
	global_load_dwordx4 v[88:91], v[56:57], off offset:1024
	global_load_dwordx4 v[92:95], v[58:59], off offset:1024
	s_waitcnt vmcnt(39)
	v_mfma_f32_16x16x32_bf16 v[4:7], v[100:103], v[96:99], v[4:7]
	v_mfma_f32_16x16x32_bf16 v[0:3], v[104:107], v[96:99], v[0:3]
	global_load_dwordx4 v[96:99], v[16:17], off offset:832
	global_load_dwordx4 v[100:103], v[56:57], off offset:1088
	global_load_dwordx4 v[104:107], v[58:59], off offset:1088
	s_waitcnt vmcnt(39)
	v_mfma_f32_16x16x32_bf16 v[4:7], v[112:115], v[108:111], v[4:7]
	v_mfma_f32_16x16x32_bf16 v[0:3], v[116:119], v[108:111], v[0:3]
	global_load_dwordx4 v[108:111], v[16:17], off offset:896
	global_load_dwordx4 v[112:115], v[56:57], off offset:1152
	global_load_dwordx4 v[116:119], v[58:59], off offset:1152
	s_waitcnt vmcnt(39)
	v_mfma_f32_16x16x32_bf16 v[4:7], v[124:127], v[120:123], v[4:7]
	v_mfma_f32_16x16x32_bf16 v[0:3], v[128:131], v[120:123], v[0:3]
	global_load_dwordx4 v[120:123], v[16:17], off offset:960
	global_load_dwordx4 v[124:127], v[56:57], off offset:1216
	global_load_dwordx4 v[128:131], v[58:59], off offset:1216
	s_waitcnt vmcnt(39)
	v_mfma_f32_16x16x32_bf16 v[4:7], v[136:139], v[132:135], v[4:7]
	v_mfma_f32_16x16x32_bf16 v[0:3], v[140:143], v[132:135], v[0:3]
	global_load_dwordx4 v[132:135], v[16:17], off offset:1024
	global_load_dwordx4 v[136:139], v[56:57], off offset:1280
	global_load_dwordx4 v[140:143], v[58:59], off offset:1280
	s_waitcnt vmcnt(39)
	v_mfma_f32_16x16x32_bf16 v[4:7], v[148:151], v[144:147], v[4:7]
	v_mfma_f32_16x16x32_bf16 v[0:3], v[152:155], v[144:147], v[0:3]
	global_load_dwordx4 v[144:147], v[16:17], off offset:1088
	global_load_dwordx4 v[148:151], v[56:57], off offset:1344
	global_load_dwordx4 v[152:155], v[58:59], off offset:1344
	s_waitcnt vmcnt(39)
	v_mfma_f32_16x16x32_bf16 v[4:7], v[164:167], v[160:163], v[4:7]
	v_mfma_f32_16x16x32_bf16 v[0:3], v[168:171], v[160:163], v[0:3]
	global_load_dwordx4 v[160:163], v[16:17], off offset:1152
	global_load_dwordx4 v[164:167], v[56:57], off offset:1408
	global_load_dwordx4 v[168:171], v[58:59], off offset:1408
	s_waitcnt vmcnt(39)
; __device__ __forceinline__ unsigned pk2(float lo, float hi) { f32x2_t v = {lo, hi}; bf16x2_t b = __builtin_convertvector(v, bf16x2_t); return __builtin_bit_cast(unsigned, b); }
; template <class F>
; __device__ __forceinline__ void mini_gemm64(const bf16_t* __restrict__ A, const bf16_t* __restrict__ Bt, int wave, int lane, F&& epi) {
;     ...
;     for (int ks = 0; ks < 32; ++ks) {
;         const bf16x8 a = *(const bf16x8*)(ap + ks * 32), x0 = *(const bf16x8*)(b0 + ks * 32), x1 = *(const bf16x8*)(b1 + ks * 32);
;         acc0 = __builtin_amdgcn_mfma_f32_16x16x32_bf16(x0, a, acc0, 0, 0, 0);
;         acc1 = __builtin_amdgcn_mfma_f32_16x16x32_bf16(x1, a, acc1, 0, 0, 0);
;     }
;     const int row = 16 * (wave >> 1) + fr, col = 32 * (wave & 1) + 4 * fq;
;     epi(row, col, acc0); epi(row, col + 16, acc1);
; __global__ void __launch_bounds__(512, 2) hymba_fwd(Params Parg) {
;     ...
;                 [&](int row, int col, f32x4 v) {
;                     u32x2 w; w.x = pk2(v[0], v[1]); w.y = pk2(v[2], v[3]);
;                     *(u32x2*)(mo + (size_t)(MP + rg * 64 + row) * 1024 + cg * 64 + col) = w;
;                 });
	v_mfma_f32_16x16x32_bf16 v[4:7], v[180:183], v[172:175], v[4:7]
	v_mfma_f32_16x16x32_bf16 v[0:3], v[186:189], v[172:175], v[0:3]
	global_load_dwordx4 v[172:175], v[16:17], off offset:1216
	global_load_dwordx4 v[180:183], v[56:57], off offset:1472
	global_load_dwordx4 v[186:189], v[58:59], off offset:1472
	s_waitcnt vmcnt(39)
	v_mfma_f32_16x16x32_bf16 v[4:7], v[194:197], v[190:193], v[4:7]
	v_mfma_f32_16x16x32_bf16 v[0:3], v[198:201], v[190:193], v[0:3]
	global_load_dwordx4 v[190:193], v[16:17], off offset:1280
	global_load_dwordx4 v[194:197], v[56:57], off offset:1536
	global_load_dwordx4 v[198:201], v[58:59], off offset:1536
	s_waitcnt vmcnt(39)
	v_mfma_f32_16x16x32_bf16 v[4:7], v[206:209], v[202:205], v[4:7]
	v_mfma_f32_16x16x32_bf16 v[0:3], v[210:213], v[202:205], v[0:3]
	global_load_dwordx4 v[202:205], v[16:17], off offset:1344
	global_load_dwordx4 v[206:209], v[56:57], off offset:1600
	global_load_dwordx4 v[210:213], v[58:59], off offset:1600
	s_waitcnt vmcnt(39)
	v_mfma_f32_16x16x32_bf16 v[4:7], v[218:221], v[214:217], v[4:7]
	v_mfma_f32_16x16x32_bf16 v[0:3], v[222:225], v[214:217], v[0:3]
	global_load_dwordx4 v[214:217], v[16:17], off offset:1408
	global_load_dwordx4 v[218:221], v[56:57], off offset:1664
	global_load_dwordx4 v[222:225], v[58:59], off offset:1664
	s_waitcnt vmcnt(39)
	v_mfma_f32_16x16x32_bf16 v[4:7], v[230:233], v[226:229], v[4:7]
	v_mfma_f32_16x16x32_bf16 v[0:3], v[234:237], v[226:229], v[0:3]
	global_load_dwordx4 v[226:229], v[16:17], off offset:1472
	global_load_dwordx4 v[230:233], v[56:57], off offset:1728
	global_load_dwordx4 v[234:237], v[58:59], off offset:1728
	s_waitcnt vmcnt(39)
	v_mfma_f32_16x16x32_bf16 v[4:7], v[64:67], v[60:63], v[4:7]
	v_mfma_f32_16x16x32_bf16 v[0:3], v[68:71], v[60:63], v[0:3]
	global_load_dwordx4 v[60:63], v[16:17], off offset:1536
	global_load_dwordx4 v[64:67], v[56:57], off offset:1792
	global_load_dwordx4 v[68:71], v[58:59], off offset:1792
	s_waitcnt vmcnt(39)
	v_mfma_f32_16x16x32_bf16 v[4:7], v[76:79], v[72:75], v[4:7]
	v_mfma_f32_16x16x32_bf16 v[0:3], v[80:83], v[72:75], v[0:3]
	global_load_dwordx4 v[72:75], v[16:17], off offset:1600
	global_load_dwordx4 v[76:79], v[56:57], off offset:1856
	global_load_dwordx4 v[80:83], v[58:59], off offset:1856
	s_waitcnt vmcnt(39)
	v_mfma_f32_16x16x32_bf16 v[4:7], v[88:91], v[84:87], v[4:7]
	v_mfma_f32_16x16x32_bf16 v[0:3], v[92:95], v[84:87], v[0:3]
	global_load_dwordx4 v[84:87], v[16:17], off offset:1664
	global_load_dwordx4 v[88:91], v[56:57], off offset:1920
	global_load_dwordx4 v[92:95], v[58:59], off offset:1920
	s_waitcnt vmcnt(39)
	v_mfma_f32_16x16x32_bf16 v[4:7], v[100:103], v[96:99], v[4:7]
	v_mfma_f32_16x16x32_bf16 v[0:3], v[104:107], v[96:99], v[0:3]
	global_load_dwordx4 v[96:99], v[16:17], off offset:1728
	global_load_dwordx4 v[100:103], v[56:57], off offset:1984
	global_load_dwordx4 v[104:107], v[58:59], off offset:1984
	s_waitcnt vmcnt(39)
	v_mfma_f32_16x16x32_bf16 v[4:7], v[112:115], v[108:111], v[4:7]
	v_mfma_f32_16x16x32_bf16 v[0:3], v[116:119], v[108:111], v[0:3]
	s_waitcnt vmcnt(36)
	v_mfma_f32_16x16x32_bf16 v[4:7], v[124:127], v[120:123], v[4:7]
	v_mfma_f32_16x16x32_bf16 v[0:3], v[128:131], v[120:123], v[0:3]
	s_waitcnt vmcnt(33)
	v_mfma_f32_16x16x32_bf16 v[4:7], v[136:139], v[132:135], v[4:7]
	v_mfma_f32_16x16x32_bf16 v[0:3], v[140:143], v[132:135], v[0:3]
	s_waitcnt vmcnt(30)
	v_mfma_f32_16x16x32_bf16 v[4:7], v[148:151], v[144:147], v[4:7]
	v_mfma_f32_16x16x32_bf16 v[0:3], v[152:155], v[144:147], v[0:3]
	s_waitcnt vmcnt(27)
	v_mfma_f32_16x16x32_bf16 v[4:7], v[164:167], v[160:163], v[4:7]
	v_mfma_f32_16x16x32_bf16 v[0:3], v[168:171], v[160:163], v[0:3]
	s_waitcnt vmcnt(24)
	v_mfma_f32_16x16x32_bf16 v[4:7], v[180:183], v[172:175], v[4:7]
	v_mfma_f32_16x16x32_bf16 v[0:3], v[186:189], v[172:175], v[0:3]
	s_waitcnt vmcnt(21)
	v_mfma_f32_16x16x32_bf16 v[4:7], v[194:197], v[190:193], v[4:7]
	v_mfma_f32_16x16x32_bf16 v[0:3], v[198:201], v[190:193], v[0:3]
	s_waitcnt vmcnt(18)
	v_mfma_f32_16x16x32_bf16 v[4:7], v[206:209], v[202:205], v[4:7]
	v_mfma_f32_16x16x32_bf16 v[0:3], v[210:213], v[202:205], v[0:3]
	s_waitcnt vmcnt(15)
	v_mfma_f32_16x16x32_bf16 v[4:7], v[218:221], v[214:217], v[4:7]
	v_mfma_f32_16x16x32_bf16 v[0:3], v[222:225], v[214:217], v[0:3]
	s_waitcnt vmcnt(12)
	v_mfma_f32_16x16x32_bf16 v[4:7], v[230:233], v[226:229], v[4:7]
	v_mfma_f32_16x16x32_bf16 v[0:3], v[234:237], v[226:229], v[0:3]
	s_waitcnt vmcnt(9)
	v_mfma_f32_16x16x32_bf16 v[4:7], v[64:67], v[60:63], v[4:7]
	v_mfma_f32_16x16x32_bf16 v[0:3], v[68:71], v[60:63], v[0:3]
	s_waitcnt vmcnt(6)
	v_mfma_f32_16x16x32_bf16 v[4:7], v[76:79], v[72:75], v[4:7]
	v_mfma_f32_16x16x32_bf16 v[0:3], v[80:83], v[72:75], v[0:3]
	s_waitcnt vmcnt(3)
	v_mfma_f32_16x16x32_bf16 v[4:7], v[88:91], v[84:87], v[4:7]
	v_mfma_f32_16x16x32_bf16 v[0:3], v[92:95], v[84:87], v[0:3]
	s_waitcnt vmcnt(0)
	v_mfma_f32_16x16x32_bf16 v[4:7], v[100:103], v[96:99], v[4:7]
	v_mfma_f32_16x16x32_bf16 v[0:3], v[104:107], v[96:99], v[0:3]
	s_nop 7
	s_mov_b64 s[8:9], 0x800
	s_lshl_b32 s4, s10, 6
	s_and_b32 s4, s4, 0xc0
	v_add_u32_e32 v8, s4, v22
	s_nop 1
	v_cvt_pk_bf16_f32 v4, v4, v5
	v_cvt_pk_bf16_f32 v5, v6, v7
	v_lshlrev_b64 v[6:7], 11, v[8:9]
	s_lshl_b32 s6, s6, 6
	v_lshl_add_u64 v[6:7], s[0:1], 0, v[6:7]
	s_ashr_i32 s7, s6, 31
	v_lshl_add_u64 v[6:7], s[6:7], 1, v[6:7]
	v_mov_b32_e32 v15, v9
	s_add_i32 s10, s10, s94
	s_add_i32 s2, s2, s3
	v_lshl_add_u64 v[6:7], v[6:7], 0, v[14:15]
	v_cvt_pk_bf16_f32 v0, v0, v1
	v_cvt_pk_bf16_f32 v1, v2, v3
	s_cmp_gt_i32 s10, 63
	global_store_dwordx2 v[6:7], v[4:5], off
	global_store_dwordx2 v[6:7], v[0:1], off offset:32
	s_cbranch_scc0 .LBB0_713
	v_mov_b32_e32 v8, v21
